# MLA attention key-tile loop body rewritten: K/V fragment reads issued ahead of the MFMAs, score accumulators start from -m_ref (no per-score subtraction)
# speedup vs baseline: 1.0100x; 1.0100x over previous
; DI int TID() { int t = (int)__builtin_amdgcn_workitem_id_x(); asm volatile("" : "+v"(t)); return t; }
; template <int DQK, int DV, bool BAND> ...
;     ...
;   const int tid = TID(), lane = tid & 63, w = tid >> 6, r32 = lane & 31, hi = lane >> 5;
;   u16* Ks = (u16*)smem; u16* Vs = (u16*)(smem + 17408); float* sc = (float*)(smem + 34816) + w * 64;
;   const int qw0 = q0 + w * 32, qi = qw0 + r32;
;   bf16x8 qf[ND0];
; #pragma unroll
;   for (int d0 = 0; d0 < ND0; ++d0) qf[d0] = *(const bf16x8*)(Q + (size_t)(w * 32 + r32) * ldq + d0 * 16 + hi * 8);
;   f32x16 o[NCB];
; #pragma unroll
;   for (int cb = 0; cb < NCB; ++cb)
; #pragma unroll
;     for (int r = 0; r < 16; ++r) o[cb][r] = 0.f;
;   float m_run = -INFINITY, l_run = 0.f;
;   int kt_lo = 0, kt_hi = nkeys >> 6;
;   if (BAND) { kt_lo = max(0, (q0 >> 6) - 1); kt_hi = min(nkeys >> 6, (q0 >> 6) + 3); }
;   u32x4 kreg[KCH], vreg[VCH];
;     ...
;   constexpr bool PREF = true;
;   if (PREF) ALOAD(kt_lo);
; DI void item_attn(const Params& p, int l, const Chunk& ck, int it, char* smem) {
;     ...
;     const int rnd = it >> 9, x = it & 7, jj = (it & 511) >> 3; const int qs = ck.sshift - 7, ppx = 64 >> qs;
;     const int bh = rnd * (8 * ppx) + x * ppx + (jj >> qs), qblk = jj & ((1 << qs) - 1);
;     const int h = bh & 7, bl = bh >> 3; const int t0 = qblk * 128, lt0 = bl * S + t0;
;     const u16* Q = (const u16*)(p.ws + OFF_QM) + (size_t)lt0 * 768 + h * 96;
;     const u16* K = (const u16*)(p.ws + OFF_KM) + (size_t)(bl * S) * 768 + h * 96;
;     const u16* Vt = (const u16*)(p.ws + OFF_VMT) + ((size_t)(bl * 8 + h) * 64) * S;
;     u16* O = (u16*)(p.ws + OFF_BR) + (size_t)(1 * CT + lt0) * 512 + h * 64;
;     (void)t0;
;     attn_block<96, 64, false>(Q, 768, K, 768, Vt, S, S, t0, 0.f, O, 512, nullptr, 0, smem);
.LBB1_317:
	s_ashr_i32 s21, s55, 6
	s_and_b32 s0, s55, 7
	s_and_b32 s29, s21, -8
	s_bfe_u32 s20, s55, 0x60003
	s_or_b32 s0, s29, s0
	s_lshr_b32 s30, s20, s35
	s_mul_i32 s0, s0, s42
	s_add_i32 s21, s0, s30
	s_and_b32 s20, s20, s43
	s_ashr_i32 s22, s21, 3
	s_lshl_b32 s20, s20, 7
	s_mul_i32 s26, s22, s2
	s_add_i32 s20, s26, s20
	s_and_b32 s28, s16, 7
	s_and_b32 s0, s21, 7
	s_mul_i32 s23, s20, 0x600
	s_mul_hi_i32 s22, s20, 0x600
	s_add_u32 s23, s93, s23
	s_addc_u32 s24, s94, s22
	s_mul_i32 s27, s0, 0xc0
	s_add_u32 s22, s23, s27
	v_mov_b32_e32 v2, v172
	s_addc_u32 s23, s24, 0
	s_mul_hi_i32 s25, s74, s21
	s_mul_i32 s24, s74, s21
	s_movk_i32 s21, 0xffe0
	v_ashrrev_i32_e32 v0, 1, v2
	v_bfe_u32 v3, v2, 5, 1
	s_waitcnt vmcnt(9)
	v_and_b32_e32 v122, 0xffffffe0, v0
	v_bfi_b32 v0, s21, v0, v2
	v_mov_b64_e32 v[4:5], s[22:23]
	s_movk_i32 s31, 0x600
	v_mad_i64_i32 v[4:5], s[22:23], v0, s31, v[4:5]
	v_lshlrev_b32_e32 v0, 4, v3
	v_lshl_add_u64 v[4:5], v[4:5], 0, v[0:1]
	global_load_dwordx4 v[66:69], v[4:5], off
	global_load_dwordx4 v[70:73], v[4:5], off offset:32
	global_load_dwordx4 v[74:77], v[4:5], off offset:64
	global_load_dwordx4 v[78:81], v[4:5], off offset:96
	global_load_dwordx4 v[82:85], v[4:5], off offset:128
	global_load_dwordx4 v[86:89], v[4:5], off offset:160
	v_lshlrev_b32_e32 v4, 2, v2
	s_mov_b32 s21, 0x2aaaaaab
	v_and_b32_e32 v29, 0xffffff00, v4
	v_mul_hi_i32 v4, v2, s21
	v_lshrrev_b32_e32 v5, 31, v4
	v_ashrrev_i32_e32 v4, 1, v4
	v_add_u32_e32 v30, v4, v5
	v_add_u32_e32 v4, 0x100, v2
	v_mul_hi_i32 v5, v4, s21
	v_lshrrev_b32_e32 v6, 31, v5
	v_ashrrev_i32_e32 v5, 1, v5
	v_add_u32_e32 v31, v5, v6
	v_add_u32_e32 v6, 0x200, v2
	s_lshl_b64 s[24:25], s[24:25], 1
	v_mul_hi_i32 v5, v6, s21
	v_ashrrev_i32_e32 v12, 3, v2
	s_waitcnt lgkmcnt(0)
	v_ashrrev_i32_e32 v16, 3, v4
	s_add_u32 s24, s17, s24
	v_lshrrev_b32_e32 v7, 31, v5
	v_ashrrev_i32_e32 v5, 1, v5
	v_mad_i64_i32 v[14:15], s[22:23], v12, s2, 0
	v_mad_i64_i32 v[18:19], s[22:23], v16, s2, 0
	s_addc_u32 s25, s34, s25
	v_add_u32_e32 v36, v5, v7
	v_lshlrev_b32_e32 v5, 4, v2
	s_mul_i32 s22, s26, 0x600
	v_and_b32_e32 v8, 0x70, v5
	v_mov_b32_e32 v9, v1
	s_mul_hi_i32 s23, s26, 0x600
	s_add_u32 s21, s79, s22
	v_lshl_add_u64 v[10:11], s[24:25], 0, v[8:9]
	s_addc_u32 s25, s92, s23
	s_add_u32 s24, s21, s27
	v_mad_u64_u32 v[6:7], s[26:27], v36, -12, v[6:7]
	s_addc_u32 s25, s25, 0
	v_lshlrev_b32_e32 v20, 3, v6
	v_mad_u64_u32 v[4:5], s[26:27], v31, -12, v[4:5]
	v_lshl_add_u64 v[18:19], v[18:19], 1, v[10:11]
	v_lshl_add_u64 v[10:11], v[14:15], 1, v[10:11]
	v_ashrrev_i32_e32 v21, 31, v20
	v_lshlrev_b32_e32 v22, 3, v4
	v_mad_u64_u32 v[24:25], s[26:27], v30, -12, v[2:3]
	global_load_dwordx4 v[94:97], v[18:19], off
	global_load_dwordx4 v[90:93], v[10:11], off
	v_mov_b64_e32 v[10:11], s[24:25]
	v_ashrrev_i32_e32 v23, 31, v22
	v_lshlrev_b32_e32 v26, 3, v24
	v_mad_i64_i32 v[14:15], s[24:25], v36, s31, v[10:11]
	v_lshlrev_b64 v[18:19], 1, v[20:21]
	v_ashrrev_i32_e32 v27, 31, v26
	v_lshl_add_u64 v[14:15], v[14:15], 0, v[18:19]
	v_mad_i64_i32 v[20:21], s[24:25], v31, s31, v[10:11]
	v_lshlrev_b64 v[22:23], 1, v[22:23]
	v_lshl_add_u64 v[20:21], v[20:21], 0, v[22:23]
	global_load_dwordx4 v[102:105], v[14:15], off
	global_load_dwordx4 v[98:101], v[20:21], off
	v_mad_i64_i32 v[10:11], s[24:25], v30, s31, v[10:11]
	v_lshlrev_b64 v[14:15], 1, v[26:27]
	v_lshl_add_u64 v[10:11], v[10:11], 0, v[14:15]
	global_load_dwordx4 v[106:109], v[10:11], off
	s_movk_i32 s24, 0xd0
	s_movk_i32 s26, 0x88
	v_mul_lo_u32 v38, v30, s24
	v_mul_lo_u32 v40, v31, s24
	v_mul_lo_u32 v42, v36, s24
	v_mad_u64_u32 v[32:33], s[24:25], v12, s26, v[8:9]
	v_mad_u64_u32 v[34:35], s[24:25], v16, s26, v[8:9]
	s_or_b32 s24, s29, s28
	s_mul_i32 s24, s42, s24
	s_add_i32 s24, s30, s24
	s_ashr_i32 s25, s24, 31
	v_and_b32_e32 v121, 31, v2
	v_ashrrev_i32_e32 v13, 31, v12
	v_or_b32_e32 v120, v29, v0
	s_lshl_b64 s[24:25], s[24:25], 7
	v_and_b32_e32 v0, 7, v2
	v_lshlrev_b32_e32 v28, 3, v3
	v_cmp_eq_u32_e64 s[36:37], 0, v3
	v_lshlrev_b32_e32 v123, 2, v3
	v_mul_u32_u24_e32 v3, 0x44, v121
	v_lshlrev_b32_e32 v39, 4, v4
	v_lshl_add_u64 v[4:5], v[12:13], 1, s[24:25]
	v_lshlrev_b32_e32 v0, 4, v0
	v_lshl_add_u32 v125, v3, 1, v28
	v_mad_u64_u32 v[2:3], s[26:27], s2, v4, v[0:1]
	v_ashrrev_i32_e32 v17, 31, v16
	v_mad_i32_i24 v3, s2, v5, v3
	s_mov_b64 s[26:27], 0x15080080
	v_lshl_add_u64 v[110:111], v[2:3], 0, s[26:27]
	v_lshl_add_u64 v[2:3], v[16:17], 1, s[24:25]
	v_mad_u64_u32 v[4:5], s[24:25], s2, v2, v[0:1]
	v_mad_i32_i24 v5, s2, v3, v5
	v_mov_b64_e32 v[2:3], s[22:23]
	v_lshl_add_u64 v[112:113], v[4:5], 0, s[26:27]
	v_mad_i64_i32 v[4:5], s[22:23], v36, s31, v[2:3]
	s_mov_b64 s[26:27], 0x13898000
	s_add_i32 s22, s54, s30
	v_lshl_add_u64 v[4:5], v[4:5], 0, s[26:27]
	s_and_b32 s24, s22, 7
	v_mad_u64_u32 v[4:5], s[22:23], s24, v203, v[4:5]
	s_waitcnt vmcnt(19)
; template <int DQK, int DV, bool BAND> ...
;     ...
;   f32x16 o[NCB];
; #pragma unroll
;   for (int cb = 0; cb < NCB; ++cb)
; #pragma unroll
;     for (int r = 0; r < 16; ++r) o[cb][r] = 0.f;
;   float m_run = -INFINITY, l_run = 0.f;
;   int kt_lo = 0, kt_hi = nkeys >> 6;
;   if (BAND) { kt_lo = max(0, (q0 >> 6) - 1); kt_hi = min(nkeys >> 6, (q0 >> 6) + 3); }
;   u32x4 kreg[KCH], vreg[VCH];
;     ...
;   constexpr bool PREF = true;
;   if (PREF) ALOAD(kt_lo);
	v_lshl_add_u64 v[114:115], v[4:5], 0, v[18:19]
	v_mad_i64_i32 v[4:5], s[22:23], v31, s31, v[2:3]
	v_mad_i64_i32 v[2:3], s[22:23], v30, s31, v[2:3]
	v_lshl_add_u64 v[4:5], v[4:5], 0, s[26:27]
	v_lshl_add_u64 v[2:3], v[2:3], 0, s[26:27]
	v_mad_u64_u32 v[4:5], s[22:23], s24, v203, v[4:5]
	v_mad_u64_u32 v[2:3], s[22:23], s24, v203, v[2:3]
	v_lshl_or_b32 v124, v121, 2, v29
	v_lshlrev_b32_e32 v37, 4, v24
	v_lshlrev_b32_e32 v41, 4, v6
	v_add_u32_e32 v33, v28, v28
	v_mul_u32_u24_e32 v35, 0xd0, v121
	v_lshl_add_u64 v[116:117], v[4:5], 0, v[22:23]
	v_lshl_add_u64 v[118:119], v[2:3], 0, v[14:15]
	v_mov_b32_e32 v2, v1
	v_mov_b32_e32 v3, v1
	v_mov_b32_e32 v4, v1
	v_mov_b32_e32 v5, v1
	v_mov_b32_e32 v6, v1
	v_mov_b32_e32 v7, v1
	v_mov_b32_e32 v8, v1
	v_mov_b32_e32 v10, v1
	v_mov_b32_e32 v11, v1
	v_mov_b32_e32 v12, v1
	v_mov_b32_e32 v13, v1
	v_mov_b32_e32 v14, v1
	v_mov_b32_e32 v15, v1
	v_mov_b32_e32 v16, v1
	v_mov_b32_e32 v17, v1
	v_mov_b32_e32 v18, v1
	v_mov_b32_e32 v19, v1
	v_mov_b32_e32 v20, v1
	v_mov_b32_e32 v21, v1
	v_mov_b32_e32 v22, v1
	v_mov_b32_e32 v23, v1
	v_mov_b32_e32 v24, v1
	v_mov_b32_e32 v25, v1
	v_mov_b32_e32 v26, v1
	v_mov_b32_e32 v27, v1
	v_mov_b32_e32 v28, v1
	v_mov_b32_e32 v29, v1
	v_mov_b32_e32 v30, v1
	v_mov_b32_e32 v31, v1
	v_mov_b32_e32 v0, v1
	v_add_u32_e32 v130, 0x4400, v32
	v_add_u32_e32 v132, v33, v35
	v_mov_b64_e32 v[32:33], v[30:31]
	s_mov_b32 s21, 0
	s_waitcnt vmcnt(18)
	v_mov_b32_e32 v126, 0
	v_mov_b32_e32 v133, 0xff800000
	v_add_u32_e32 v127, v37, v38
	v_add_u32_e32 v128, v39, v40
	v_add_u32_e32 v129, v41, v42
	v_add_u32_e32 v131, 0x4400, v34
	v_mov_b64_e32 v[30:31], v[28:29]
	v_mov_b64_e32 v[28:29], v[26:27]
	v_mov_b64_e32 v[26:27], v[24:25]
	v_mov_b64_e32 v[24:25], v[22:23]
	v_mov_b64_e32 v[22:23], v[20:21]
	v_mov_b64_e32 v[20:21], v[18:19]
	v_mov_b64_e32 v[18:19], v[16:17]
	v_mov_b64_e32 v[16:17], v[14:15]
	v_mov_b64_e32 v[14:15], v[12:13]
	v_mov_b64_e32 v[12:13], v[10:11]
	v_mov_b64_e32 v[10:11], v[8:9]
	v_mov_b64_e32 v[8:9], v[6:7]
	v_mov_b64_e32 v[6:7], v[4:5]
	v_mov_b64_e32 v[4:5], v[2:3]
	v_mov_b64_e32 v[2:3], v[0:1]
	v_mov_b32_e32 v150, 0
	v_mov_b32_e32 v151, 0
	v_mov_b32_e32 v152, 0
	v_mov_b32_e32 v153, 0
	v_mov_b32_e32 v154, 0
	v_mov_b32_e32 v155, 0
	v_mov_b32_e32 v156, 0
	v_mov_b32_e32 v157, 0
	v_mov_b32_e32 v158, 0
	v_mov_b32_e32 v159, 0
	v_mov_b32_e32 v160, 0
	v_mov_b32_e32 v161, 0
	v_mov_b32_e32 v162, 0
	v_mov_b32_e32 v163, 0
	v_mov_b32_e32 v164, 0
	v_mov_b32_e32 v165, 0

; #define MFMA(a, b, c) __builtin_amdgcn_mfma_f32_32x32x16_bf16((a), (b), (c), 0, 0, 0)
; DI float xhalf_max(float x) { const auto rr = __builtin_amdgcn_permlane32_swap(__float_as_uint(x), __float_as_uint(x), false, false); return fmaxf(__uint_as_float(rr[0]), __uint_as_float(rr[1])); }
; template <int DQK, int DV, bool BAND> ...
;     ...
;     if constexpr (DQK < 128) {
;       f32x16 p0, p1;
; #pragma unroll
;       for (int r = 0; r < 16; ++r) { p0[r] = 0.f; p1[r] = 0.f; }
;       __builtin_amdgcn_s_setprio(1);
; #pragma unroll
;       for (int d0 = 0; d0 < ND0; ++d0) {
;         const bf16x8 k0f = *(const bf16x8*)&Ks[r32 * KLD + d0 * 16 + hi * 8];
;         const bf16x8 k1f = *(const bf16x8*)&Ks[(32 + r32) * KLD + d0 * 16 + hi * 8];
;         p0 = MFMA(k0f, qf[d0], p0); p1 = MFMA(k1f, qf[d0], p1);
;       }
;       __builtin_amdgcn_s_setprio(0);
;       float mx = fmaxf(p0[0], p1[0]);
; #pragma unroll
;       for (int r = 1; r < 16; ++r) mx = fmaxf(mx, fmaxf(p0[r], p1[r]));
;       mx = xhalf_max(mx);
;       if (__builtin_amdgcn_ballot_w64(mx > m_run + 8.f) != 0ull) {
;         const float m_new = fmaxf(m_run, mx); const float m_use = (m_new == -INFINITY) ? 0.f : m_new;
;         const float alpha = __builtin_amdgcn_exp2f(m_run - m_use);
;         l_run *= alpha; m_run = m_new;
;         if (hi == 0) sc[r32] = alpha;
;         __builtin_amdgcn_fence(__ATOMIC_RELEASE, "wavefront");
;         __builtin_amdgcn_wave_barrier();
; #pragma unroll
;         for (int g4 = 0; g4 < 4; ++g4) { const f32x4 a4 = *(const f32x4*)&sc[8 * g4 + 4 * hi];
; #pragma unroll
;           for (int cb = 0; cb < NCB; ++cb)
; #pragma unroll
;             for (int j = 0; j < 4; ++j) o[cb][4 * g4 + j] *= a4[j]; }
;         __builtin_amdgcn_wave_barrier();
;       }
;       const float m_ref = (m_run == -INFINITY) ? 0.f : m_run;
.LBB1_320:
	s_setprio 1
	ds_read_b128 v[208:211], v132
	ds_read_b128 v[212:215], v132 offset:6656
	ds_read_b128 v[216:219], v132 offset:32
	ds_read_b128 v[220:223], v132 offset:6688
	ds_read_b128 v[224:227], v132 offset:64
	ds_read_b128 v[228:231], v132 offset:6720
	ds_read_b128 v[232:235], v132 offset:96
	ds_read_b128 v[236:239], v132 offset:6752
	ds_read_b128 v[240:243], v132 offset:128
	ds_read_b128 v[244:247], v132 offset:6784
	ds_read_b128 v[248:251], v132 offset:160
	ds_read_b128 v[134:137], v132 offset:6816
	v_add_u32_e32 v166, 0x4000, v125
	v_add_u32_e32 v167, 0x5000, v125
	s_waitcnt lgkmcnt(11)
	v_mfma_f32_32x32x16_bf16 v[34:49], v[208:211], v[66:69], v[150:165]
	s_waitcnt lgkmcnt(10)
	v_mfma_f32_32x32x16_bf16 v[50:65], v[212:215], v[66:69], v[150:165]
	s_waitcnt lgkmcnt(9)
	v_mfma_f32_32x32x16_bf16 v[34:49], v[216:219], v[70:73], v[34:49]
	s_waitcnt lgkmcnt(8)
	v_mfma_f32_32x32x16_bf16 v[50:65], v[220:223], v[70:73], v[50:65]
	s_waitcnt lgkmcnt(7)
	v_mfma_f32_32x32x16_bf16 v[34:49], v[224:227], v[74:77], v[34:49]
	s_waitcnt lgkmcnt(6)
	v_mfma_f32_32x32x16_bf16 v[50:65], v[228:231], v[74:77], v[50:65]
	s_waitcnt lgkmcnt(5)
	v_mfma_f32_32x32x16_bf16 v[34:49], v[232:235], v[78:81], v[34:49]
	s_waitcnt lgkmcnt(4)
	v_mfma_f32_32x32x16_bf16 v[50:65], v[236:239], v[78:81], v[50:65]
	s_waitcnt lgkmcnt(3)
	v_mfma_f32_32x32x16_bf16 v[34:49], v[240:243], v[82:85], v[34:49]
	s_waitcnt lgkmcnt(2)
	v_mfma_f32_32x32x16_bf16 v[50:65], v[244:247], v[82:85], v[50:65]
	s_waitcnt lgkmcnt(1)
	v_mfma_f32_32x32x16_bf16 v[34:49], v[248:251], v[86:89], v[34:49]
	s_waitcnt lgkmcnt(0)
	v_mfma_f32_32x32x16_bf16 v[50:65], v[134:137], v[86:89], v[50:65]
	s_setprio 0
	ds_read2_b64 v[208:211], v166 offset0:128 offset1:130
	ds_read2_b64 v[212:215], v167 offset0:160 offset1:162
	ds_read2_b64 v[216:219], v166 offset0:136 offset1:138
	ds_read2_b64 v[220:223], v167 offset0:168 offset1:170
	ds_read2_b64 v[224:227], v166 offset0:132 offset1:134
	ds_read2_b64 v[228:231], v167 offset0:164 offset1:166
	ds_read2_b64 v[232:235], v166 offset0:140 offset1:142
	ds_read2_b64 v[236:239], v167 offset0:172 offset1:174
	s_nop 10
	v_max3_f32 v0, v34, v50, v35
	v_max3_f32 v134, v51, v36, v52
	v_max3_f32 v0, v0, v37, v53
	v_max3_f32 v134, v134, v38, v54
	v_max3_f32 v0, v0, v39, v55
	v_max3_f32 v134, v134, v40, v56
	v_max3_f32 v0, v0, v41, v57
	v_max3_f32 v134, v134, v42, v58
	v_max3_f32 v0, v0, v43, v59
	v_max3_f32 v134, v134, v44, v60
	v_max3_f32 v0, v0, v45, v61
	v_max3_f32 v134, v134, v46, v62
	v_max3_f32 v0, v0, v47, v63
	v_max3_f32 v134, v134, v48, v64
	v_max3_f32 v0, v0, v49, v65
	v_max_f32_e32 v0, v0, v134
	v_mov_b32_e32 v134, v0
	s_nop 1
	v_permlane32_swap_b32_e32 v0, v134
	v_max_f32_e32 v0, v0, v134
	v_sub_f32_e32 v0, v0, v150
	v_add_f32_e32 v134, 0x41000000, v133
	v_cmp_gt_f32_e32 vcc, v0, v134
	s_cbranch_vccz .LBB1_324
	v_max_f32_e32 v0, v0, v0
	v_max_f32_e32 v134, v133, v133
	v_max_f32_e32 v0, v134, v0
	v_cmp_neq_f32_e32 vcc, s7, v0
	s_nop 1
	v_cndmask_b32_e32 v134, 0, v0, vcc
	v_sub_f32_e32 v133, v133, v134
	v_exp_f32_e32 v133, v133
	v_add_f32_e32 v168, v150, v134
	s_and_saveexec_b64 s[22:23], s[36:37]
	ds_write_b32 v124, v133 offset:34816
	s_or_b64 exec, exec, s[22:23]
	s_waitcnt lgkmcnt(0)
	ds_read_b128 v[136:139], v120 offset:34816
	ds_read_b128 v[140:143], v120 offset:34848
	ds_read_b128 v[144:147], v120 offset:34880
	ds_read_b128 v[240:243], v120 offset:34912
	v_mul_f32_e32 v126, v126, v133
	v_sub_f32_e32 v34, v34, v168
	v_sub_f32_e32 v35, v35, v168
	v_sub_f32_e32 v36, v36, v168
	v_sub_f32_e32 v37, v37, v168
	v_sub_f32_e32 v38, v38, v168
	v_sub_f32_e32 v39, v39, v168
	v_sub_f32_e32 v40, v40, v168
	v_sub_f32_e32 v41, v41, v168
	v_sub_f32_e32 v42, v42, v168
	v_sub_f32_e32 v43, v43, v168
	v_sub_f32_e32 v44, v44, v168
	v_sub_f32_e32 v45, v45, v168
	v_sub_f32_e32 v46, v46, v168
	v_sub_f32_e32 v47, v47, v168
	v_sub_f32_e32 v48, v48, v168
	v_sub_f32_e32 v49, v49, v168
	v_sub_f32_e32 v50, v50, v168
	v_sub_f32_e32 v51, v51, v168
	v_sub_f32_e32 v52, v52, v168
	v_sub_f32_e32 v53, v53, v168
	v_sub_f32_e32 v54, v54, v168
	v_sub_f32_e32 v55, v55, v168
	v_sub_f32_e32 v56, v56, v168
	v_sub_f32_e32 v57, v57, v168
	v_sub_f32_e32 v58, v58, v168
	v_sub_f32_e32 v59, v59, v168
	v_sub_f32_e32 v60, v60, v168
	v_sub_f32_e32 v61, v61, v168
	v_sub_f32_e32 v62, v62, v168
	v_sub_f32_e32 v63, v63, v168
	v_sub_f32_e32 v64, v64, v168
	v_sub_f32_e32 v65, v65, v168
	v_sub_f32_e32 v150, 0, v134
	v_mov_b32_e32 v151, v150
	v_mov_b32_e32 v152, v150
	v_mov_b32_e32 v153, v150
	v_mov_b32_e32 v154, v150
	v_mov_b32_e32 v155, v150
	v_mov_b32_e32 v156, v150
	v_mov_b32_e32 v157, v150
	v_mov_b32_e32 v158, v150
	v_mov_b32_e32 v159, v150
	v_mov_b32_e32 v160, v150
	v_mov_b32_e32 v161, v150
	v_mov_b32_e32 v162, v150
	v_mov_b32_e32 v163, v150
	v_mov_b32_e32 v164, v150
	v_mov_b32_e32 v165, v150
	s_waitcnt lgkmcnt(0)
	v_pk_mul_f32 v[2:3], v[2:3], v[136:137]
	v_pk_mul_f32 v[4:5], v[4:5], v[138:139]
	v_pk_mul_f32 v[6:7], v[6:7], v[140:141]
	v_pk_mul_f32 v[8:9], v[8:9], v[142:143]
	v_pk_mul_f32 v[10:11], v[10:11], v[144:145]
	v_pk_mul_f32 v[12:13], v[12:13], v[146:147]
	v_pk_mul_f32 v[14:15], v[14:15], v[240:241]
	v_pk_mul_f32 v[16:17], v[16:17], v[242:243]
	v_pk_mul_f32 v[18:19], v[18:19], v[136:137]
	v_pk_mul_f32 v[20:21], v[20:21], v[138:139]
	v_pk_mul_f32 v[22:23], v[22:23], v[140:141]
	v_pk_mul_f32 v[24:25], v[24:25], v[142:143]
	v_pk_mul_f32 v[26:27], v[26:27], v[144:145]
	v_pk_mul_f32 v[28:29], v[28:29], v[146:147]
	v_pk_mul_f32 v[30:31], v[30:31], v[240:241]
	v_pk_mul_f32 v[32:33], v[32:33], v[242:243]
	s_branch .LBB1_325

; #define MFMA(a, b, c) __builtin_amdgcn_mfma_f32_32x32x16_bf16((a), (b), (c), 0, 0, 0)
; DI unsigned pk2(float a, float b) { f2_t v = {a, b}; bf2_t r = __builtin_convertvector(v, bf2_t); return __builtin_bit_cast(unsigned, r); }
; DI float xhalf_sum(float x) { const auto rr = __builtin_amdgcn_permlane32_swap(__float_as_uint(x), __float_as_uint(x), false, false); return __uint_as_float(rr[0]) + __uint_as_float(rr[1]); }
; template <int DQK, int DV, bool BAND> ...
;     ...
;       const float m_ref = (m_run == -INFINITY) ? 0.f : m_run;
;       float rs0 = 0.f, rs1 = 0.f;
; #pragma unroll
;       for (int r = 0; r < 16; ++r) { const float e0 = __builtin_amdgcn_exp2f(p0[r] - m_ref), e1 = __builtin_amdgcn_exp2f(p1[r] - m_ref); p0[r] = e0; p1[r] = e1; rs0 += e0; rs1 += e1; }
;       l_run += xhalf_sum(rs0 + rs1);
;       __builtin_amdgcn_s_setprio(1);
; #pragma unroll
;       for (int s = 0; s < 2; ++s) {
;         const u32x4 pu0 = {pk2(p0[8 * s], p0[8 * s + 1]), pk2(p0[8 * s + 2], p0[8 * s + 3]), pk2(p0[8 * s + 4], p0[8 * s + 5]), pk2(p0[8 * s + 6], p0[8 * s + 7])};
;         const u32x4 pu1 = {pk2(p1[8 * s], p1[8 * s + 1]), pk2(p1[8 * s + 2], p1[8 * s + 3]), pk2(p1[8 * s + 4], p1[8 * s + 5]), pk2(p1[8 * s + 6], p1[8 * s + 7])};
; #pragma unroll
;         for (int cb = 0; cb < NCB; ++cb) {
;           const u32x2 lo0 = *(const u32x2*)&Vs[(cb * 32 + r32) * VLD + 16 * s + 4 * hi];
;           const u32x2 hi0 = *(const u32x2*)&Vs[(cb * 32 + r32) * VLD + 16 * s + 4 * hi + 8];
;           const u32x4 v0 = {lo0[0], lo0[1], hi0[0], hi0[1]};
;           o[cb] = MFMA(__builtin_bit_cast(bf16x8, pu0), __builtin_bit_cast(bf16x8, v0), o[cb]);
;         }
; #pragma unroll
;         for (int cb = 0; cb < NCB; ++cb) {
;           const u32x2 lo1 = *(const u32x2*)&Vs[(cb * 32 + r32) * VLD + 32 + 16 * s + 4 * hi];
;           const u32x2 hi1 = *(const u32x2*)&Vs[(cb * 32 + r32) * VLD + 32 + 16 * s + 4 * hi + 8];
;           const u32x4 v1 = {lo1[0], lo1[1], hi1[0], hi1[1]};
;           o[cb] = MFMA(__builtin_bit_cast(bf16x8, pu1), __builtin_bit_cast(bf16x8, v1), o[cb]);
;         }
;       }
;       __builtin_amdgcn_s_setprio(0);
.LBB1_325:
	v_exp_f32_e32 v34, v34
	v_exp_f32_e32 v35, v35
	v_exp_f32_e32 v36, v36
	v_exp_f32_e32 v37, v37
	v_exp_f32_e32 v38, v38
	v_exp_f32_e32 v39, v39
	v_exp_f32_e32 v40, v40
	v_exp_f32_e32 v41, v41
	v_exp_f32_e32 v42, v42
	v_exp_f32_e32 v43, v43
	v_exp_f32_e32 v44, v44
	v_exp_f32_e32 v45, v45
	v_exp_f32_e32 v46, v46
	v_exp_f32_e32 v47, v47
	v_exp_f32_e32 v48, v48
	v_exp_f32_e32 v49, v49
	v_exp_f32_e32 v50, v50
	v_exp_f32_e32 v51, v51
	v_exp_f32_e32 v52, v52
	v_exp_f32_e32 v53, v53
	v_exp_f32_e32 v54, v54
	v_exp_f32_e32 v55, v55
	v_exp_f32_e32 v56, v56
	v_exp_f32_e32 v57, v57
	v_exp_f32_e32 v58, v58
	v_exp_f32_e32 v59, v59
	v_exp_f32_e32 v60, v60
	v_exp_f32_e32 v61, v61
	v_exp_f32_e32 v62, v62
	v_exp_f32_e32 v63, v63
	v_exp_f32_e32 v64, v64
	v_exp_f32_e32 v65, v65
	s_nop 0
	v_pk_add_f32 v[168:169], v[34:35], v[36:37]
	v_pk_add_f32 v[170:171], v[38:39], v[40:41]
	v_pk_add_f32 v[168:169], v[42:43], v[168:169]
	v_pk_add_f32 v[170:171], v[44:45], v[170:171]
	v_pk_add_f32 v[168:169], v[46:47], v[168:169]
	v_pk_add_f32 v[170:171], v[48:49], v[170:171]
	v_pk_add_f32 v[168:169], v[50:51], v[168:169]
	v_pk_add_f32 v[170:171], v[52:53], v[170:171]
	v_pk_add_f32 v[168:169], v[54:55], v[168:169]
	v_pk_add_f32 v[170:171], v[56:57], v[170:171]
	v_pk_add_f32 v[168:169], v[58:59], v[168:169]
	v_pk_add_f32 v[170:171], v[60:61], v[170:171]
	v_pk_add_f32 v[168:169], v[62:63], v[168:169]
	v_pk_add_f32 v[170:171], v[64:65], v[170:171]
	v_pk_add_f32 v[168:169], v[168:169], v[170:171]
	s_nop 0
	v_add_f32_e32 v168, v168, v169
	v_mov_b32_e32 v169, v168
	s_nop 1
	v_permlane32_swap_b32_e32 v168, v169
	v_add_f32_e32 v168, v168, v169
	v_add_f32_e32 v126, v126, v168
	v_cvt_pk_bf16_f32 v34, v34, v35
	v_cvt_pk_bf16_f32 v35, v36, v37
	v_cvt_pk_bf16_f32 v36, v38, v39
	v_cvt_pk_bf16_f32 v37, v40, v41
	v_cvt_pk_bf16_f32 v38, v42, v43
	v_cvt_pk_bf16_f32 v39, v44, v45
	v_cvt_pk_bf16_f32 v40, v46, v47
	v_cvt_pk_bf16_f32 v41, v48, v49
	v_cvt_pk_bf16_f32 v50, v50, v51
	v_cvt_pk_bf16_f32 v51, v52, v53
	v_cvt_pk_bf16_f32 v52, v54, v55
	v_cvt_pk_bf16_f32 v53, v56, v57
	v_cvt_pk_bf16_f32 v54, v58, v59
	v_cvt_pk_bf16_f32 v55, v60, v61
	v_cvt_pk_bf16_f32 v56, v62, v63
	v_cvt_pk_bf16_f32 v57, v64, v65
	s_setprio 1
	s_waitcnt lgkmcnt(0)
	v_mfma_f32_32x32x16_bf16 v[2:17], v[34:37], v[208:211], v[2:17]
	v_mfma_f32_32x32x16_bf16 v[18:33], v[34:37], v[212:215], v[18:33]
	v_mfma_f32_32x32x16_bf16 v[2:17], v[50:53], v[216:219], v[2:17]
	v_mfma_f32_32x32x16_bf16 v[18:33], v[50:53], v[220:223], v[18:33]
	v_mfma_f32_32x32x16_bf16 v[2:17], v[38:41], v[224:227], v[2:17]
	v_mfma_f32_32x32x16_bf16 v[18:33], v[38:41], v[228:231], v[18:33]
	v_mfma_f32_32x32x16_bf16 v[2:17], v[54:57], v[232:235], v[2:17]
	v_mfma_f32_32x32x16_bf16 v[18:33], v[54:57], v[236:239], v[18:33]
	s_setprio 0
	v_lshl_add_u64 v[110:111], v[110:111], 0, s[8:9]
	v_lshl_add_u64 v[112:113], v[112:113], 0, s[8:9]
	v_lshl_add_u64 v[114:115], v[114:115], 0, s[10:11]
	v_lshl_add_u64 v[116:117], v[116:117], 0, s[10:11]
	s_cmp_eq_u32 s75, s21
	v_lshl_add_u64 v[118:119], v[118:119], 0, s[10:11]
	s_cbranch_scc1 .LBB1_327
	v_mov_b32_e32 v133, v0
	s_branch .LBB1_318
